# fused-LN GEMM: last K-iteration peeled, its 14 trailing K-tile re-read DMAs now prefetch the residual XB tile rows into the freed LDS slots; post-loop residual fetch reduced to 2 DMAs per wave
# speedup vs baseline: 1.0053x; 1.0053x over previous
; #define PG8_STAGE(bufoff, gbase, voff) do { _Pragma("unroll") for (int _i = 0; _i < 2; ++_i) \
;         __builtin_amdgcn_global_load_lds((const unsigned*)((const char*)(gbase) + (voff)[_i]), (PG8_LAS unsigned*)(lds + (bufoff) + ldsw + _i * 8192), 16, 0, 0); } while (0)
; #define PG8_LDA(dst, b, h) do { _Pragma("unroll") for (int m = 0; m < 4; ++m) _Pragma("unroll") for (int k = 0; k < 2; ++k) dst[m][k] = *(const PG8_LAS bf16x8*)(lds + PG8_SA(b, h) + aoff + m * 2048 + k * 1024); } while (0)
; #define PG8_LDB(dst, b, h) do { _Pragma("unroll") for (int n = 0; n < 2; ++n) _Pragma("unroll") for (int k = 0; k < 2; ++k) dst[n][k] = *(const PG8_LAS bf16x8*)(lds + PG8_SB(b, h) + boff + n * 2048 + k * 1024); } while (0)
; #define PG8_MMA(ai, bj, At, Bt) do { __builtin_amdgcn_s_setprio(1); _Pragma("unroll") for (int m = 0; m < 4; ++m) _Pragma("unroll") for (int n = 0; n < 2; ++n) _Pragma("unroll") for (int k = 0; k < 2; ++k) \
;         acc[ai][bj][m][n] = __builtin_amdgcn_mfma_f32_16x16x32_bf16(Bt[n][k], At[m][k], acc[ai][bj][m][n], 0, 0, 0); __builtin_amdgcn_s_setprio(0); } while (0)
; #define PG8_WAIT_V(n) asm volatile("s_waitcnt vmcnt(" #n ")" ::: "memory")
; #define PG8_BAR __builtin_amdgcn_s_barrier()
; template <class Epi, class Sched, bool ALIGN_EPI = false, bool SP2 = false>
; __device__ __forceinline__ void gemm_phase(PG8_LAS unsigned char* lds, const Gemm g, const Sched& S, const Epi& E) {
;     ...
;         for (int t = 0; t < nt; t += 2) {
;             const bool last = (t == nt - 2);
;             const char* a1 = cA + (size_t)(t + 1) * kstep;
;             const char* a2 = last ? nA : cA + (size_t)(t + 2) * kstep; const char* b2 = last ? nB : cB + (size_t)(t + 2) * kstep;
;             const char* a3 = a2 + kstep; const char* b3 = b2 + kstep;
;             if (last && has_next) S.a_ready(nxt);
;             if constexpr (SP2) {
;             PG8_LDB(B0, 0, 0); PG8_LDB(B1, 0, 1); PG8_SCHED; PG8_LDA(At, 0, 0); PG8_STAGE(PG8_SA(1, 1), a1 + hstep, voffA);
;             PG8_WAIT_V(8); PG8_WAIT_L(0); PG8_BAR; PG8_MMA(0, 0, At, B0); PG8_MMA(0, 1, At, B1); PG8_BAR; PG8_SCHED;
;             PG8_LDA(At, 0, 1); PG8_STAGE(PG8_SB(0, 0), b2, voffB); PG8_STAGE(PG8_SB(0, 1), b2 + hstep, voffB); PG8_STAGE(PG8_SA(0, 0), a2, voffA);
;             PG8_WAIT_V(8); PG8_WAIT_L(0); PG8_BAR; PG8_MMA(1, 0, At, B0); PG8_MMA(1, 1, At, B1); PG8_BAR; PG8_SCHED;
.LBB11_1896:
	s_cmp_eq_u32 s49, s22
	s_cbranch_scc1 .Lpeel_fused
	s_add_i32 s56, s22, 2
	s_add_u32 s57, s16, s20
	s_addc_u32 s23, s17, s21
	s_add_u32 s58, s14, s20
	s_addc_u32 s59, s15, s21
	s_add_i32 s60, 0, 0x10000
	s_cmp_eq_u32 s49, s22
	s_cselect_b32 s23, s5, s23
	s_cselect_b32 s22, s4, s57
	s_cselect_b32 s59, s19, s59
	s_cselect_b32 s58, s18, s58
	s_add_i32 s57, 0, 0x14000
	v_add_u32_e32 v156, s60, v1
	v_add_u32_e32 v174, s57, v1
	ds_read_b128 v[144:147], v156
	ds_read_b128 v[148:151], v156 offset:1024
	ds_read_b128 v[152:155], v156 offset:2048
	ds_read_b128 v[156:159], v156 offset:3072
	ds_read_b128 v[160:163], v174
	ds_read_b128 v[166:169], v174 offset:1024
	ds_read_b128 v[170:173], v174 offset:2048
	ds_read_b128 v[174:177], v174 offset:3072
	v_lshl_add_u64 v[184:185], s[16:17], 0, v[140:141]
	s_add_i32 m0, s45, 0xc000
	ds_read_b128 v[178:181], v143
	ds_read_b128 v[198:201], v143 offset:1024
	ds_read_b128 v[202:205], v143 offset:2048
	ds_read_b128 v[220:223], v143 offset:3072
	ds_read_b128 v[224:227], v143 offset:4096
	ds_read_b128 v[228:231], v143 offset:5120
	ds_read_b128 v[232:235], v143 offset:6144
	ds_read_b128 v[236:239], v143 offset:7168
	global_load_lds_dwordx4 v[184:185], off
	v_lshl_add_u64 v[184:185], s[16:17], 0, v[138:139]
	s_add_i32 m0, s45, 0xe000
	s_nop 0
	global_load_lds_dwordx4 v[184:185], off
	s_waitcnt vmcnt(8)
	s_waitcnt lgkmcnt(0)
	s_barrier
	s_setprio 1
	s_waitcnt lgkmcnt(0)
	v_mfma_f32_16x16x32_bf16 v[100:103], v[144:147], v[178:181], v[100:103]
	v_mfma_f32_16x16x32_bf16 v[68:71], v[152:155], v[178:181], v[68:71]
	v_mfma_f32_16x16x32_bf16 v[116:119], v[144:147], v[202:205], v[116:119]
	v_mfma_f32_16x16x32_bf16 v[80:83], v[152:155], v[202:205], v[80:83]
	v_mfma_f32_16x16x32_bf16 v[124:127], v[144:147], v[224:227], v[124:127]
	v_mfma_f32_16x16x32_bf16 v[104:107], v[152:155], v[224:227], v[104:107]
	v_mfma_f32_16x16x32_bf16 v[128:131], v[144:147], v[232:235], v[128:131]
	v_mfma_f32_16x16x32_bf16 v[120:123], v[152:155], v[232:235], v[120:123]
	v_mfma_f32_16x16x32_bf16 v[100:103], v[148:151], v[198:201], v[100:103]
	v_mfma_f32_16x16x32_bf16 v[68:71], v[156:159], v[198:201], v[68:71]
	v_mfma_f32_16x16x32_bf16 v[116:119], v[148:151], v[220:223], v[116:119]
	v_mfma_f32_16x16x32_bf16 v[80:83], v[156:159], v[220:223], v[80:83]
	v_mfma_f32_16x16x32_bf16 v[124:127], v[148:151], v[228:231], v[124:127]
	v_mfma_f32_16x16x32_bf16 v[104:107], v[156:159], v[228:231], v[104:107]
	v_mfma_f32_16x16x32_bf16 v[128:131], v[148:151], v[236:239], v[128:131]
	v_mfma_f32_16x16x32_bf16 v[120:123], v[156:159], v[236:239], v[120:123]
	s_setprio 0
	s_setprio 1
	v_mfma_f32_16x16x32_bf16 v[16:19], v[160:163], v[178:181], v[16:19]
	v_mfma_f32_16x16x32_bf16 v[4:7], v[170:173], v[178:181], v[4:7]
	v_mfma_f32_16x16x32_bf16 v[32:35], v[160:163], v[202:205], v[32:35]
	v_mfma_f32_16x16x32_bf16 v[8:11], v[170:173], v[202:205], v[8:11]
	v_mfma_f32_16x16x32_bf16 v[48:51], v[160:163], v[224:227], v[48:51]
	v_mfma_f32_16x16x32_bf16 v[12:15], v[170:173], v[224:227], v[12:15]
	v_mfma_f32_16x16x32_bf16 v[76:79], v[160:163], v[232:235], v[76:79]
	v_mfma_f32_16x16x32_bf16 v[24:27], v[170:173], v[232:235], v[24:27]
	v_mfma_f32_16x16x32_bf16 v[16:19], v[166:169], v[198:201], v[16:19]
	v_mfma_f32_16x16x32_bf16 v[4:7], v[174:177], v[198:201], v[4:7]
	v_mfma_f32_16x16x32_bf16 v[32:35], v[166:169], v[220:223], v[32:35]
	v_mfma_f32_16x16x32_bf16 v[8:11], v[174:177], v[220:223], v[8:11]
	v_mfma_f32_16x16x32_bf16 v[48:51], v[166:169], v[228:231], v[48:51]
	v_mfma_f32_16x16x32_bf16 v[12:15], v[174:177], v[228:231], v[12:15]
	v_mfma_f32_16x16x32_bf16 v[76:79], v[166:169], v[236:239], v[76:79]
	v_mfma_f32_16x16x32_bf16 v[24:27], v[174:177], v[236:239], v[24:27]
	s_setprio 0
	s_barrier
	s_add_i32 s60, s60, s13
	v_lshl_add_u64 v[184:185], s[58:59], 0, v[2:3]
	s_mov_b32 m0, s60
	ds_read_b128 v[178:181], v143 offset:16384
	ds_read_b128 v[198:201], v143 offset:17408
	ds_read_b128 v[202:205], v143 offset:18432
	ds_read_b128 v[220:223], v143 offset:19456
	ds_read_b128 v[224:227], v143 offset:20480
	ds_read_b128 v[228:231], v143 offset:21504
	ds_read_b128 v[232:235], v143 offset:22528
	ds_read_b128 v[236:239], v143 offset:23552
	global_load_lds_dwordx4 v[184:185], off
	s_add_i32 m0, s60, 0x2000
	v_lshl_add_u64 v[186:187], s[58:59], 0, v[132:133]
	s_add_u32 s58, s58, s33
	s_addc_u32 s59, s59, 0
	s_add_i32 s57, s57, s13
	global_load_lds_dwordx4 v[186:187], off
	v_lshl_add_u64 v[196:197], s[58:59], 0, v[2:3]
	s_mov_b32 m0, s57
	v_lshl_add_u64 v[206:207], s[58:59], 0, v[132:133]
	global_load_lds_dwordx4 v[196:197], off
	s_add_i32 m0, s57, 0x2000
	v_lshl_add_u64 v[240:241], s[22:23], 0, v[2:3]
	global_load_lds_dwordx4 v[206:207], off
	s_mov_b32 m0, s45
	v_lshl_add_u64 v[242:243], s[22:23], 0, v[132:133]
	global_load_lds_dwordx4 v[240:241], off
	s_mov_b32 m0, s46
	s_nop 0
	global_load_lds_dwordx4 v[242:243], off
	s_waitcnt vmcnt(8)
	s_waitcnt lgkmcnt(0)
	s_barrier
; #define PG8_STAGE(bufoff, gbase, voff) do { _Pragma("unroll") for (int _i = 0; _i < 2; ++_i) \
;         __builtin_amdgcn_global_load_lds((const unsigned*)((const char*)(gbase) + (voff)[_i]), (PG8_LAS unsigned*)(lds + (bufoff) + ldsw + _i * 8192), 16, 0, 0); } while (0)
; #define PG8_LDA(dst, b, h) do { _Pragma("unroll") for (int m = 0; m < 4; ++m) _Pragma("unroll") for (int k = 0; k < 2; ++k) dst[m][k] = *(const PG8_LAS bf16x8*)(lds + PG8_SA(b, h) + aoff + m * 2048 + k * 1024); } while (0)
; #define PG8_LDB(dst, b, h) do { _Pragma("unroll") for (int n = 0; n < 2; ++n) _Pragma("unroll") for (int k = 0; k < 2; ++k) dst[n][k] = *(const PG8_LAS bf16x8*)(lds + PG8_SB(b, h) + boff + n * 2048 + k * 1024); } while (0)
; #define PG8_MMA(ai, bj, At, Bt) do { __builtin_amdgcn_s_setprio(1); _Pragma("unroll") for (int m = 0; m < 4; ++m) _Pragma("unroll") for (int n = 0; n < 2; ++n) _Pragma("unroll") for (int k = 0; k < 2; ++k) \
;         acc[ai][bj][m][n] = __builtin_amdgcn_mfma_f32_16x16x32_bf16(Bt[n][k], At[m][k], acc[ai][bj][m][n], 0, 0, 0); __builtin_amdgcn_s_setprio(0); } while (0)
; #define PG8_WAIT_V(n) asm volatile("s_waitcnt vmcnt(" #n ")" ::: "memory")
; #define PG8_WAIT_L(n) asm volatile("s_waitcnt lgkmcnt(" #n ")" ::: "memory")
; #define PG8_BAR __builtin_amdgcn_s_barrier()
; #define PG8_SCHED __builtin_amdgcn_sched_barrier(0)
; template <class Epi, class Sched, bool ALIGN_EPI = false, bool SP2 = false>
; __device__ __forceinline__ void gemm_phase(PG8_LAS unsigned char* lds, const Gemm g, const Sched& S, const Epi& E) {
;     ...
;             PG8_WAIT_V(8); PG8_WAIT_L(0); PG8_BAR; PG8_MMA(1, 0, At, B0); PG8_MMA(1, 1, At, B1); PG8_BAR; PG8_SCHED;
;             PG8_LDB(B0, 1, 0); PG8_LDB(B1, 1, 1); PG8_SCHED; PG8_LDA(At, 1, 0); PG8_STAGE(PG8_SA(0, 1), a2 + hstep, voffA);
;             PG8_WAIT_V(8); PG8_WAIT_L(0); PG8_BAR; PG8_MMA(0, 0, At, B0); PG8_MMA(0, 1, At, B1); PG8_BAR; PG8_SCHED;
;             PG8_LDA(At, 1, 1); PG8_STAGE(PG8_SB(1, 0), b3, voffB); PG8_STAGE(PG8_SB(1, 1), b3 + hstep, voffB); PG8_STAGE(PG8_SA(1, 0), a3, voffA);
	s_setprio 1
	s_waitcnt lgkmcnt(0)
	v_mfma_f32_16x16x32_bf16 v[108:111], v[144:147], v[178:181], v[108:111]
	v_mfma_f32_16x16x32_bf16 v[112:115], v[152:155], v[178:181], v[112:115]
	v_mfma_f32_16x16x32_bf16 v[88:91], v[144:147], v[202:205], v[88:91]
	v_mfma_f32_16x16x32_bf16 v[92:95], v[152:155], v[202:205], v[92:95]
	v_mfma_f32_16x16x32_bf16 v[60:63], v[144:147], v[224:227], v[60:63]
	v_mfma_f32_16x16x32_bf16 v[64:67], v[152:155], v[224:227], v[64:67]
	v_mfma_f32_16x16x32_bf16 v[36:39], v[144:147], v[232:235], v[36:39]
	v_mfma_f32_16x16x32_bf16 v[40:43], v[152:155], v[232:235], v[40:43]
	v_mfma_f32_16x16x32_bf16 v[108:111], v[148:151], v[198:201], v[108:111]
	v_mfma_f32_16x16x32_bf16 v[112:115], v[156:159], v[198:201], v[112:115]
	v_mfma_f32_16x16x32_bf16 v[88:91], v[148:151], v[220:223], v[88:91]
	v_mfma_f32_16x16x32_bf16 v[92:95], v[156:159], v[220:223], v[92:95]
	v_mfma_f32_16x16x32_bf16 v[60:63], v[148:151], v[228:231], v[60:63]
	v_mfma_f32_16x16x32_bf16 v[64:67], v[156:159], v[228:231], v[64:67]
	v_mfma_f32_16x16x32_bf16 v[36:39], v[148:151], v[236:239], v[36:39]
	v_mfma_f32_16x16x32_bf16 v[40:43], v[156:159], v[236:239], v[40:43]
	s_setprio 0
	s_setprio 1
	v_mfma_f32_16x16x32_bf16 v[96:99], v[160:163], v[178:181], v[96:99]
	v_mfma_f32_16x16x32_bf16 v[44:47], v[170:173], v[178:181], v[44:47]
	v_mfma_f32_16x16x32_bf16 v[84:87], v[160:163], v[202:205], v[84:87]
	v_mfma_f32_16x16x32_bf16 v[72:75], v[170:173], v[202:205], v[72:75]
	v_mfma_f32_16x16x32_bf16 v[56:59], v[160:163], v[224:227], v[56:59]
	v_mfma_f32_16x16x32_bf16 v[52:55], v[170:173], v[224:227], v[52:55]
	v_mfma_f32_16x16x32_bf16 v[28:31], v[160:163], v[232:235], v[28:31]
	v_mfma_f32_16x16x32_bf16 v[20:23], v[170:173], v[232:235], v[20:23]
	v_mfma_f32_16x16x32_bf16 v[96:99], v[166:169], v[198:201], v[96:99]
	v_mfma_f32_16x16x32_bf16 v[44:47], v[174:177], v[198:201], v[44:47]
	v_mfma_f32_16x16x32_bf16 v[84:87], v[166:169], v[220:223], v[84:87]
	v_mfma_f32_16x16x32_bf16 v[72:75], v[174:177], v[220:223], v[72:75]
	v_mfma_f32_16x16x32_bf16 v[56:59], v[166:169], v[228:231], v[56:59]
	v_mfma_f32_16x16x32_bf16 v[52:55], v[174:177], v[228:231], v[52:55]
	v_mfma_f32_16x16x32_bf16 v[28:31], v[166:169], v[236:239], v[28:31]
	v_mfma_f32_16x16x32_bf16 v[20:23], v[174:177], v[236:239], v[20:23]
	s_setprio 0
	s_barrier
	s_add_i32 s57, 0, 0x18000
	s_add_i32 s58, 0, 0x1c000
	v_add_u32_e32 v156, s57, v1
	v_add_u32_e32 v174, s58, v1
	ds_read_b128 v[144:147], v156
	ds_read_b128 v[148:151], v156 offset:1024
	ds_read_b128 v[152:155], v156 offset:2048
	ds_read_b128 v[156:159], v156 offset:3072
	ds_read_b128 v[160:163], v174
	ds_read_b128 v[166:169], v174 offset:1024
	ds_read_b128 v[170:173], v174 offset:2048
	ds_read_b128 v[174:177], v174 offset:3072
	s_add_u32 s22, s22, s33
	s_addc_u32 s23, s23, 0
	s_mov_b32 m0, s47
	v_lshl_add_u64 v[244:245], s[22:23], 0, v[2:3]
	ds_read_b128 v[178:181], v143 offset:32768
	ds_read_b128 v[198:201], v143 offset:33792
	ds_read_b128 v[202:205], v143 offset:34816
	ds_read_b128 v[220:223], v143 offset:35840
	ds_read_b128 v[224:227], v143 offset:36864
	ds_read_b128 v[228:231], v143 offset:37888
	ds_read_b128 v[232:235], v143 offset:38912
	ds_read_b128 v[236:239], v143 offset:39936
	global_load_lds_dwordx4 v[244:245], off
	v_lshl_add_u64 v[244:245], s[22:23], 0, v[132:133]
	s_mov_b32 m0, s48
	s_nop 0
	global_load_lds_dwordx4 v[244:245], off
	s_waitcnt vmcnt(8)
	s_waitcnt lgkmcnt(0)
	s_barrier
	s_setprio 1
	s_waitcnt lgkmcnt(0)
	v_mfma_f32_16x16x32_bf16 v[100:103], v[144:147], v[178:181], v[100:103]
	v_mfma_f32_16x16x32_bf16 v[68:71], v[152:155], v[178:181], v[68:71]
	v_mfma_f32_16x16x32_bf16 v[116:119], v[144:147], v[202:205], v[116:119]
	v_mfma_f32_16x16x32_bf16 v[80:83], v[152:155], v[202:205], v[80:83]
	v_mfma_f32_16x16x32_bf16 v[124:127], v[144:147], v[224:227], v[124:127]
	v_mfma_f32_16x16x32_bf16 v[104:107], v[152:155], v[224:227], v[104:107]
	v_mfma_f32_16x16x32_bf16 v[128:131], v[144:147], v[232:235], v[128:131]
	v_mfma_f32_16x16x32_bf16 v[120:123], v[152:155], v[232:235], v[120:123]
	v_mfma_f32_16x16x32_bf16 v[100:103], v[148:151], v[198:201], v[100:103]
	v_mfma_f32_16x16x32_bf16 v[68:71], v[156:159], v[198:201], v[68:71]
	v_mfma_f32_16x16x32_bf16 v[116:119], v[148:151], v[220:223], v[116:119]
	v_mfma_f32_16x16x32_bf16 v[80:83], v[156:159], v[220:223], v[80:83]
	v_mfma_f32_16x16x32_bf16 v[124:127], v[148:151], v[228:231], v[124:127]
	v_mfma_f32_16x16x32_bf16 v[104:107], v[156:159], v[228:231], v[104:107]
	v_mfma_f32_16x16x32_bf16 v[128:131], v[148:151], v[236:239], v[128:131]
	v_mfma_f32_16x16x32_bf16 v[120:123], v[156:159], v[236:239], v[120:123]
	s_setprio 0
	s_setprio 1
	v_mfma_f32_16x16x32_bf16 v[16:19], v[160:163], v[178:181], v[16:19]
	v_mfma_f32_16x16x32_bf16 v[4:7], v[170:173], v[178:181], v[4:7]
	v_mfma_f32_16x16x32_bf16 v[32:35], v[160:163], v[202:205], v[32:35]
	v_mfma_f32_16x16x32_bf16 v[8:11], v[170:173], v[202:205], v[8:11]
	v_mfma_f32_16x16x32_bf16 v[48:51], v[160:163], v[224:227], v[48:51]
	v_mfma_f32_16x16x32_bf16 v[12:15], v[170:173], v[224:227], v[12:15]
	v_mfma_f32_16x16x32_bf16 v[76:79], v[160:163], v[232:235], v[76:79]
	v_mfma_f32_16x16x32_bf16 v[24:27], v[170:173], v[232:235], v[24:27]
	v_mfma_f32_16x16x32_bf16 v[16:19], v[166:169], v[198:201], v[16:19]
	v_mfma_f32_16x16x32_bf16 v[4:7], v[174:177], v[198:201], v[4:7]
	v_mfma_f32_16x16x32_bf16 v[32:35], v[166:169], v[220:223], v[32:35]
	v_mfma_f32_16x16x32_bf16 v[8:11], v[174:177], v[220:223], v[8:11]
	v_mfma_f32_16x16x32_bf16 v[48:51], v[166:169], v[228:231], v[48:51]
	v_mfma_f32_16x16x32_bf16 v[12:15], v[174:177], v[228:231], v[12:15]
	v_mfma_f32_16x16x32_bf16 v[76:79], v[166:169], v[236:239], v[76:79]
	v_mfma_f32_16x16x32_bf16 v[24:27], v[174:177], v[236:239], v[24:27]
	s_setprio 0
	s_barrier
; #define PG8_STAGE(bufoff, gbase, voff) do { _Pragma("unroll") for (int _i = 0; _i < 2; ++_i) \
;         __builtin_amdgcn_global_load_lds((const unsigned*)((const char*)(gbase) + (voff)[_i]), (PG8_LAS unsigned*)(lds + (bufoff) + ldsw + _i * 8192), 16, 0, 0); } while (0)
; #define PG8_LDA(dst, b, h) do { _Pragma("unroll") for (int m = 0; m < 4; ++m) _Pragma("unroll") for (int k = 0; k < 2; ++k) dst[m][k] = *(const PG8_LAS bf16x8*)(lds + PG8_SA(b, h) + aoff + m * 2048 + k * 1024); } while (0)
; #define PG8_LDB(dst, b, h) do { _Pragma("unroll") for (int n = 0; n < 2; ++n) _Pragma("unroll") for (int k = 0; k < 2; ++k) dst[n][k] = *(const PG8_LAS bf16x8*)(lds + PG8_SB(b, h) + boff + n * 2048 + k * 1024); } while (0)
; #define PG8_MMA(ai, bj, At, Bt) do { __builtin_amdgcn_s_setprio(1); _Pragma("unroll") for (int m = 0; m < 4; ++m) _Pragma("unroll") for (int n = 0; n < 2; ++n) _Pragma("unroll") for (int k = 0; k < 2; ++k) \
;         acc[ai][bj][m][n] = __builtin_amdgcn_mfma_f32_16x16x32_bf16(Bt[n][k], At[m][k], acc[ai][bj][m][n], 0, 0, 0); __builtin_amdgcn_s_setprio(0); } while (0)
; #define PG8_WAIT_V(n) asm volatile("s_waitcnt vmcnt(" #n ")" ::: "memory")
; #define PG8_WAIT_L(n) asm volatile("s_waitcnt lgkmcnt(" #n ")" ::: "memory")
; #define PG8_BAR __builtin_amdgcn_s_barrier()
; #define PG8_SCHED __builtin_amdgcn_sched_barrier(0)
; template <class Epi, class Sched, bool ALIGN_EPI = false, bool SP2 = false>
; __device__ __forceinline__ void gemm_phase(PG8_LAS unsigned char* lds, const Gemm g, const Sched& S, const Epi& E) {
;     ...
;             PG8_LDB(B0, 0, 0); PG8_LDB(B1, 0, 1); PG8_SCHED; PG8_LDA(At, 0, 0); PG8_STAGE(PG8_SA(1, 1), a1 + hstep, voffA);
;             PG8_WAIT_V(8); PG8_WAIT_L(0); PG8_BAR; PG8_MMA(0, 0, At, B0); PG8_MMA(0, 1, At, B1); PG8_BAR; PG8_SCHED;
;     ...
;             PG8_LDA(At, 1, 1); PG8_STAGE(PG8_SB(1, 0), b3, voffB); PG8_STAGE(PG8_SB(1, 1), b3 + hstep, voffB); PG8_STAGE(PG8_SA(1, 0), a3, voffA);
;             PG8_WAIT_V(8); PG8_WAIT_L(0); PG8_BAR; PG8_MMA(1, 0, At, B0); PG8_MMA(1, 1, At, B1); PG8_BAR; PG8_SCHED;
	s_add_i32 s22, s57, s13
	v_lshl_add_u64 v[184:185], v[184:185], 0, s[34:35]
	s_mov_b32 m0, s22
	ds_read_b128 v[178:181], v143 offset:49152
	ds_read_b128 v[198:201], v143 offset:50176
	ds_read_b128 v[202:205], v143 offset:51200
	ds_read_b128 v[220:223], v143 offset:52224
	ds_read_b128 v[224:227], v143 offset:53248
	ds_read_b128 v[228:231], v143 offset:54272
	ds_read_b128 v[232:235], v143 offset:55296
	ds_read_b128 v[236:239], v143 offset:56320
	global_load_lds_dwordx4 v[184:185], off
	v_lshl_add_u64 v[184:185], v[186:187], 0, s[34:35]
	s_add_i32 m0, s22, 0x2000
	s_add_i32 s22, s58, s13
	global_load_lds_dwordx4 v[184:185], off
	v_lshl_add_u64 v[184:185], v[196:197], 0, s[34:35]
	s_mov_b32 m0, s22
	s_nop 0
	global_load_lds_dwordx4 v[184:185], off
	v_lshl_add_u64 v[184:185], v[206:207], 0, s[34:35]
	s_add_i32 m0, s22, 0x2000
	s_nop 0
	global_load_lds_dwordx4 v[184:185], off
	v_lshl_add_u64 v[184:185], v[240:241], 0, s[34:35]
	s_mov_b32 m0, s50
	s_nop 0
	global_load_lds_dwordx4 v[184:185], off
	v_lshl_add_u64 v[184:185], v[242:243], 0, s[34:35]
	s_mov_b32 m0, s51
	s_nop 0
	global_load_lds_dwordx4 v[184:185], off
	s_waitcnt vmcnt(8)
	s_waitcnt lgkmcnt(0)
	s_barrier
	s_setprio 1
	s_waitcnt lgkmcnt(0)
	v_mfma_f32_16x16x32_bf16 v[108:111], v[144:147], v[178:181], v[108:111]
	v_mfma_f32_16x16x32_bf16 v[112:115], v[152:155], v[178:181], v[112:115]
	v_mfma_f32_16x16x32_bf16 v[88:91], v[144:147], v[202:205], v[88:91]
	v_mfma_f32_16x16x32_bf16 v[92:95], v[152:155], v[202:205], v[92:95]
	v_mfma_f32_16x16x32_bf16 v[60:63], v[144:147], v[224:227], v[60:63]
	v_mfma_f32_16x16x32_bf16 v[64:67], v[152:155], v[224:227], v[64:67]
	v_mfma_f32_16x16x32_bf16 v[36:39], v[144:147], v[232:235], v[36:39]
	v_mfma_f32_16x16x32_bf16 v[40:43], v[152:155], v[232:235], v[40:43]
	v_mfma_f32_16x16x32_bf16 v[108:111], v[148:151], v[198:201], v[108:111]
	v_mfma_f32_16x16x32_bf16 v[112:115], v[156:159], v[198:201], v[112:115]
	v_mfma_f32_16x16x32_bf16 v[88:91], v[148:151], v[220:223], v[88:91]
	v_mfma_f32_16x16x32_bf16 v[92:95], v[156:159], v[220:223], v[92:95]
	v_mfma_f32_16x16x32_bf16 v[60:63], v[148:151], v[228:231], v[60:63]
	v_mfma_f32_16x16x32_bf16 v[64:67], v[156:159], v[228:231], v[64:67]
	v_mfma_f32_16x16x32_bf16 v[36:39], v[148:151], v[236:239], v[36:39]
	v_mfma_f32_16x16x32_bf16 v[40:43], v[156:159], v[236:239], v[40:43]
	s_setprio 0
	s_setprio 1
	v_mfma_f32_16x16x32_bf16 v[96:99], v[160:163], v[178:181], v[96:99]
	v_mfma_f32_16x16x32_bf16 v[44:47], v[170:173], v[178:181], v[44:47]
	v_mfma_f32_16x16x32_bf16 v[84:87], v[160:163], v[202:205], v[84:87]
	v_mfma_f32_16x16x32_bf16 v[72:75], v[170:173], v[202:205], v[72:75]
	v_mfma_f32_16x16x32_bf16 v[56:59], v[160:163], v[224:227], v[56:59]
	v_mfma_f32_16x16x32_bf16 v[52:55], v[170:173], v[224:227], v[52:55]
	v_mfma_f32_16x16x32_bf16 v[28:31], v[160:163], v[232:235], v[28:31]
	v_mfma_f32_16x16x32_bf16 v[20:23], v[170:173], v[232:235], v[20:23]
	v_mfma_f32_16x16x32_bf16 v[96:99], v[166:169], v[198:201], v[96:99]
	v_mfma_f32_16x16x32_bf16 v[44:47], v[174:177], v[198:201], v[44:47]
	v_mfma_f32_16x16x32_bf16 v[84:87], v[166:169], v[220:223], v[84:87]
	v_mfma_f32_16x16x32_bf16 v[72:75], v[174:177], v[220:223], v[72:75]
	v_mfma_f32_16x16x32_bf16 v[56:59], v[166:169], v[228:231], v[56:59]
	v_mfma_f32_16x16x32_bf16 v[52:55], v[174:177], v[228:231], v[52:55]
	v_mfma_f32_16x16x32_bf16 v[28:31], v[166:169], v[236:239], v[28:31]
	v_mfma_f32_16x16x32_bf16 v[20:23], v[174:177], v[236:239], v[20:23]
	s_setprio 0
	s_barrier
	s_add_u32 s20, s20, 0x100
	s_addc_u32 s21, s21, 0
	v_lshl_add_u64 v[140:141], v[140:141], 0, s[62:63]
	v_lshl_add_u64 v[138:139], v[138:139], 0, s[62:63]
	s_cmp_ge_u32 s56, s29
	s_mov_b32 s22, s56
	s_cbranch_scc0 .LBB11_1896
	s_branch .Lpeel_done
.Lpeel_fused:
	s_add_i32 s56, s22, 2
	s_add_u32 s57, s16, s20
	s_addc_u32 s23, s17, s21
	s_add_u32 s58, s14, s20
	s_addc_u32 s59, s15, s21
	s_add_i32 s60, 0, 0x10000
	s_cmp_eq_u32 s49, s22
	s_cselect_b32 s23, s5, s23
	s_cselect_b32 s22, s4, s57
	s_cselect_b32 s59, s19, s59
	s_cselect_b32 s58, s18, s58
	s_add_i32 s57, 0, 0x14000
	v_add_u32_e32 v156, s60, v1
	v_add_u32_e32 v174, s57, v1
	ds_read_b128 v[144:147], v156
	ds_read_b128 v[148:151], v156 offset:1024
	ds_read_b128 v[152:155], v156 offset:2048
	ds_read_b128 v[156:159], v156 offset:3072
	ds_read_b128 v[160:163], v174
	ds_read_b128 v[166:169], v174 offset:1024
	ds_read_b128 v[170:173], v174 offset:2048
	ds_read_b128 v[174:177], v174 offset:3072
	v_lshl_add_u64 v[184:185], s[16:17], 0, v[140:141]
	s_add_i32 m0, s45, 0xc000
	ds_read_b128 v[178:181], v143
	ds_read_b128 v[198:201], v143 offset:1024
	ds_read_b128 v[202:205], v143 offset:2048
	ds_read_b128 v[220:223], v143 offset:3072
	ds_read_b128 v[224:227], v143 offset:4096
	ds_read_b128 v[228:231], v143 offset:5120
	ds_read_b128 v[232:235], v143 offset:6144
	ds_read_b128 v[236:239], v143 offset:7168
	global_load_lds_dwordx4 v[184:185], off
	v_lshl_add_u64 v[184:185], s[16:17], 0, v[138:139]
	s_add_i32 m0, s45, 0xe000
	s_nop 0
	global_load_lds_dwordx4 v[184:185], off
	s_waitcnt vmcnt(8)
	s_waitcnt lgkmcnt(0)
	s_barrier
; #define PG8_LAS __attribute__((address_space(3)))
; #define PG8_STAGE(bufoff, gbase, voff) do { _Pragma("unroll") for (int _i = 0; _i < 2; ++_i) \
;         __builtin_amdgcn_global_load_lds((const unsigned*)((const char*)(gbase) + (voff)[_i]), (PG8_LAS unsigned*)(lds + (bufoff) + ldsw + _i * 8192), 16, 0, 0); } while (0)
; #define PG8_LDA(dst, b, h) do { _Pragma("unroll") for (int m = 0; m < 4; ++m) _Pragma("unroll") for (int k = 0; k < 2; ++k) dst[m][k] = *(const PG8_LAS bf16x8*)(lds + PG8_SA(b, h) + aoff + m * 2048 + k * 1024); } while (0)
; #define PG8_MMA(ai, bj, At, Bt) do { __builtin_amdgcn_s_setprio(1); _Pragma("unroll") for (int m = 0; m < 4; ++m) _Pragma("unroll") for (int n = 0; n < 2; ++n) _Pragma("unroll") for (int k = 0; k < 2; ++k) \
;         acc[ai][bj][m][n] = __builtin_amdgcn_mfma_f32_16x16x32_bf16(Bt[n][k], At[m][k], acc[ai][bj][m][n], 0, 0, 0); __builtin_amdgcn_s_setprio(0); } while (0)
; #define PG8_WAIT_V(n) asm volatile("s_waitcnt vmcnt(" #n ")" ::: "memory")
; #define PG8_WAIT_L(n) asm volatile("s_waitcnt lgkmcnt(" #n ")" ::: "memory")
; #define PG8_BAR __builtin_amdgcn_s_barrier()
; #define PG8_SCHED __builtin_amdgcn_sched_barrier(0)
;     __device__ __forceinline__ void fused(f32x4 (&acc)[2][2][4][2], const Unit& u, int wr, int wc, int fr, int fq, PG8_LAS unsigned char* lds, int wid, int lane) const {
;     ...
;             for (int i = 0; i < 16; ++i) { const int c = wid * 16 + i, row = 2 * c + (lane >> 5), p = (lane & 31) ^ (row & 15);
;                 const bf16_t* src = XB + (size_t)(u.pm * BM + row) * ldc + u.pn * BM + p * 8;
;                 __builtin_amdgcn_global_load_lds((const unsigned*)src, (PG8_LAS unsigned*)(lds + c * 1024), 16, 0, 0); }
; template <class Epi, class Sched, bool ALIGN_EPI = false, bool SP2 = false>
; __device__ __forceinline__ void gemm_phase(PG8_LAS unsigned char* lds, const Gemm g, const Sched& S, const Epi& E) {
;     ...
;             PG8_WAIT_V(8); PG8_WAIT_L(0); PG8_BAR; PG8_MMA(0, 0, At, B0); PG8_MMA(0, 1, At, B1); PG8_BAR; PG8_SCHED;
;             PG8_LDA(At, 0, 1); PG8_STAGE(PG8_SB(0, 0), b2, voffB); PG8_STAGE(PG8_SB(0, 1), b2 + hstep, voffB); PG8_STAGE(PG8_SA(0, 0), a2, voffA);
;             PG8_WAIT_V(8); PG8_WAIT_L(0); PG8_BAR; PG8_MMA(1, 0, At, B0); PG8_MMA(1, 1, At, B1); PG8_BAR; PG8_SCHED;
	s_setprio 1
	s_waitcnt lgkmcnt(0)
	v_mfma_f32_16x16x32_bf16 v[100:103], v[144:147], v[178:181], v[100:103]
	v_mfma_f32_16x16x32_bf16 v[68:71], v[152:155], v[178:181], v[68:71]
	v_mfma_f32_16x16x32_bf16 v[116:119], v[144:147], v[202:205], v[116:119]
	v_mfma_f32_16x16x32_bf16 v[80:83], v[152:155], v[202:205], v[80:83]
	v_mfma_f32_16x16x32_bf16 v[124:127], v[144:147], v[224:227], v[124:127]
	v_mfma_f32_16x16x32_bf16 v[104:107], v[152:155], v[224:227], v[104:107]
	v_mfma_f32_16x16x32_bf16 v[128:131], v[144:147], v[232:235], v[128:131]
	v_mfma_f32_16x16x32_bf16 v[120:123], v[152:155], v[232:235], v[120:123]
	v_mfma_f32_16x16x32_bf16 v[100:103], v[148:151], v[198:201], v[100:103]
	v_mfma_f32_16x16x32_bf16 v[68:71], v[156:159], v[198:201], v[68:71]
	v_mfma_f32_16x16x32_bf16 v[116:119], v[148:151], v[220:223], v[116:119]
	v_mfma_f32_16x16x32_bf16 v[80:83], v[156:159], v[220:223], v[80:83]
	v_mfma_f32_16x16x32_bf16 v[124:127], v[148:151], v[228:231], v[124:127]
	v_mfma_f32_16x16x32_bf16 v[104:107], v[156:159], v[228:231], v[104:107]
	v_mfma_f32_16x16x32_bf16 v[128:131], v[148:151], v[236:239], v[128:131]
	v_mfma_f32_16x16x32_bf16 v[120:123], v[156:159], v[236:239], v[120:123]
	s_setprio 0
	s_setprio 1
	v_mfma_f32_16x16x32_bf16 v[16:19], v[160:163], v[178:181], v[16:19]
	v_mfma_f32_16x16x32_bf16 v[4:7], v[170:173], v[178:181], v[4:7]
	v_mfma_f32_16x16x32_bf16 v[32:35], v[160:163], v[202:205], v[32:35]
	v_mfma_f32_16x16x32_bf16 v[8:11], v[170:173], v[202:205], v[8:11]
	v_mfma_f32_16x16x32_bf16 v[48:51], v[160:163], v[224:227], v[48:51]
	v_mfma_f32_16x16x32_bf16 v[12:15], v[170:173], v[224:227], v[12:15]
	v_mfma_f32_16x16x32_bf16 v[76:79], v[160:163], v[232:235], v[76:79]
	v_mfma_f32_16x16x32_bf16 v[24:27], v[170:173], v[232:235], v[24:27]
	v_mfma_f32_16x16x32_bf16 v[16:19], v[166:169], v[198:201], v[16:19]
	v_mfma_f32_16x16x32_bf16 v[4:7], v[174:177], v[198:201], v[4:7]
	v_mfma_f32_16x16x32_bf16 v[32:35], v[166:169], v[220:223], v[32:35]
	v_mfma_f32_16x16x32_bf16 v[8:11], v[174:177], v[220:223], v[8:11]
	v_mfma_f32_16x16x32_bf16 v[48:51], v[166:169], v[228:231], v[48:51]
	v_mfma_f32_16x16x32_bf16 v[12:15], v[174:177], v[228:231], v[12:15]
	v_mfma_f32_16x16x32_bf16 v[76:79], v[166:169], v[236:239], v[76:79]
	v_mfma_f32_16x16x32_bf16 v[24:27], v[174:177], v[236:239], v[24:27]
	s_setprio 0
	s_barrier
	v_writelane_b32 v255, s100, 11
	v_readlane_b32 s100, v249, 31
	v_readlane_b32 s101, v249, 32
	s_add_u32 s100, s100, 0x47a00000
	s_addc_u32 s101, s101, 0
	s_lshl_b32 vcc_lo, s28, 20
	s_add_u32 s100, s100, vcc_lo
	s_addc_u32 s101, s101, 0
	s_lshl_b32 vcc_lo, s42, 9
	s_add_u32 s100, s100, vcc_lo
	s_addc_u32 s101, s101, 0
	s_lshr_b32 vcc_lo, s45, 9
	v_bfe_u32 v186, v142, 5, 1
	v_add_u32_e32 v186, vcc_lo, v186
	v_and_b32_e32 v187, 31, v142
	v_xor_b32_e32 v187, v187, v186
	v_lshlrev_b32_e32 v187, 4, v187
	v_lshl_add_u32 v186, v186, 12, v187
	s_add_i32 s60, s60, s13
	s_mov_b32 m0, s60
	ds_read_b128 v[178:181], v143 offset:16384
	ds_read_b128 v[198:201], v143 offset:17408
	ds_read_b128 v[202:205], v143 offset:18432
	ds_read_b128 v[220:223], v143 offset:19456
	ds_read_b128 v[224:227], v143 offset:20480
	ds_read_b128 v[228:231], v143 offset:21504
	ds_read_b128 v[232:235], v143 offset:22528
	ds_read_b128 v[236:239], v143 offset:23552
	s_add_u32 vcc_lo, s100, 0x80000
	s_addc_u32 vcc_hi, s101, 0
	global_load_lds_dwordx4 v186, vcc
	s_add_i32 m0, s60, 0x2000
	s_add_u32 s58, s58, s33
	s_addc_u32 s59, s59, 0
	s_add_i32 s57, s57, s13
	s_add_u32 vcc_lo, s100, 0x90000
	s_addc_u32 vcc_hi, s101, 0
	global_load_lds_dwordx4 v186, vcc
	s_mov_b32 m0, s57
	s_add_u32 vcc_lo, s100, 0xa0000
	s_addc_u32 vcc_hi, s101, 0
	global_load_lds_dwordx4 v186, vcc
	s_add_i32 m0, s57, 0x2000
	s_add_u32 vcc_lo, s100, 0xb0000
	s_addc_u32 vcc_hi, s101, 0
	global_load_lds_dwordx4 v186, vcc
	s_mov_b32 m0, s45
	s_add_u32 vcc_lo, s100, 0x0
	s_addc_u32 vcc_hi, s101, 0
	global_load_lds_dwordx4 v186, vcc
	s_mov_b32 m0, s46
	s_nop 0
	s_add_u32 vcc_lo, s100, 0x10000
	s_addc_u32 vcc_hi, s101, 0
	global_load_lds_dwordx4 v186, vcc
	s_waitcnt vmcnt(8)
	s_waitcnt lgkmcnt(0)
	s_barrier
	s_setprio 1
	s_waitcnt lgkmcnt(0)
	v_mfma_f32_16x16x32_bf16 v[108:111], v[144:147], v[178:181], v[108:111]
	v_mfma_f32_16x16x32_bf16 v[112:115], v[152:155], v[178:181], v[112:115]
	v_mfma_f32_16x16x32_bf16 v[88:91], v[144:147], v[202:205], v[88:91]
	v_mfma_f32_16x16x32_bf16 v[92:95], v[152:155], v[202:205], v[92:95]
	v_mfma_f32_16x16x32_bf16 v[60:63], v[144:147], v[224:227], v[60:63]
	v_mfma_f32_16x16x32_bf16 v[64:67], v[152:155], v[224:227], v[64:67]
	v_mfma_f32_16x16x32_bf16 v[36:39], v[144:147], v[232:235], v[36:39]
	v_mfma_f32_16x16x32_bf16 v[40:43], v[152:155], v[232:235], v[40:43]
	v_mfma_f32_16x16x32_bf16 v[108:111], v[148:151], v[198:201], v[108:111]
	v_mfma_f32_16x16x32_bf16 v[112:115], v[156:159], v[198:201], v[112:115]
	v_mfma_f32_16x16x32_bf16 v[88:91], v[148:151], v[220:223], v[88:91]
	v_mfma_f32_16x16x32_bf16 v[92:95], v[156:159], v[220:223], v[92:95]
	v_mfma_f32_16x16x32_bf16 v[60:63], v[148:151], v[228:231], v[60:63]
	v_mfma_f32_16x16x32_bf16 v[64:67], v[156:159], v[228:231], v[64:67]
	v_mfma_f32_16x16x32_bf16 v[36:39], v[148:151], v[236:239], v[36:39]
	v_mfma_f32_16x16x32_bf16 v[40:43], v[156:159], v[236:239], v[40:43]
	s_setprio 0
	s_setprio 1
	v_mfma_f32_16x16x32_bf16 v[96:99], v[160:163], v[178:181], v[96:99]
	v_mfma_f32_16x16x32_bf16 v[44:47], v[170:173], v[178:181], v[44:47]
	v_mfma_f32_16x16x32_bf16 v[84:87], v[160:163], v[202:205], v[84:87]
	v_mfma_f32_16x16x32_bf16 v[72:75], v[170:173], v[202:205], v[72:75]
	v_mfma_f32_16x16x32_bf16 v[56:59], v[160:163], v[224:227], v[56:59]
	v_mfma_f32_16x16x32_bf16 v[52:55], v[170:173], v[224:227], v[52:55]
	v_mfma_f32_16x16x32_bf16 v[28:31], v[160:163], v[232:235], v[28:31]
	v_mfma_f32_16x16x32_bf16 v[20:23], v[170:173], v[232:235], v[20:23]
	v_mfma_f32_16x16x32_bf16 v[96:99], v[166:169], v[198:201], v[96:99]
	v_mfma_f32_16x16x32_bf16 v[44:47], v[174:177], v[198:201], v[44:47]
	v_mfma_f32_16x16x32_bf16 v[84:87], v[166:169], v[220:223], v[84:87]
	v_mfma_f32_16x16x32_bf16 v[72:75], v[174:177], v[220:223], v[72:75]
	v_mfma_f32_16x16x32_bf16 v[56:59], v[166:169], v[228:231], v[56:59]
	v_mfma_f32_16x16x32_bf16 v[52:55], v[174:177], v[228:231], v[52:55]
	v_mfma_f32_16x16x32_bf16 v[28:31], v[166:169], v[236:239], v[28:31]
	v_mfma_f32_16x16x32_bf16 v[20:23], v[174:177], v[236:239], v[20:23]
	s_setprio 0
	s_barrier
; #define PG8_LAS __attribute__((address_space(3)))
; #define PG8_STAGE(bufoff, gbase, voff) do { _Pragma("unroll") for (int _i = 0; _i < 2; ++_i) \
;         __builtin_amdgcn_global_load_lds((const unsigned*)((const char*)(gbase) + (voff)[_i]), (PG8_LAS unsigned*)(lds + (bufoff) + ldsw + _i * 8192), 16, 0, 0); } while (0)
; #define PG8_LDA(dst, b, h) do { _Pragma("unroll") for (int m = 0; m < 4; ++m) _Pragma("unroll") for (int k = 0; k < 2; ++k) dst[m][k] = *(const PG8_LAS bf16x8*)(lds + PG8_SA(b, h) + aoff + m * 2048 + k * 1024); } while (0)
; #define PG8_LDB(dst, b, h) do { _Pragma("unroll") for (int n = 0; n < 2; ++n) _Pragma("unroll") for (int k = 0; k < 2; ++k) dst[n][k] = *(const PG8_LAS bf16x8*)(lds + PG8_SB(b, h) + boff + n * 2048 + k * 1024); } while (0)
; #define PG8_MMA(ai, bj, At, Bt) do { __builtin_amdgcn_s_setprio(1); _Pragma("unroll") for (int m = 0; m < 4; ++m) _Pragma("unroll") for (int n = 0; n < 2; ++n) _Pragma("unroll") for (int k = 0; k < 2; ++k) \
;         acc[ai][bj][m][n] = __builtin_amdgcn_mfma_f32_16x16x32_bf16(Bt[n][k], At[m][k], acc[ai][bj][m][n], 0, 0, 0); __builtin_amdgcn_s_setprio(0); } while (0)
;     __device__ __forceinline__ void fused(f32x4 (&acc)[2][2][4][2], const Unit& u, int wr, int wc, int fr, int fq, PG8_LAS unsigned char* lds, int wid, int lane) const {
;     ...
;             for (int i = 0; i < 16; ++i) { const int c = wid * 16 + i, row = 2 * c + (lane >> 5), p = (lane & 31) ^ (row & 15);
;                 const bf16_t* src = XB + (size_t)(u.pm * BM + row) * ldc + u.pn * BM + p * 8;
;                 __builtin_amdgcn_global_load_lds((const unsigned*)src, (PG8_LAS unsigned*)(lds + c * 1024), 16, 0, 0); }
; template <class Epi, class Sched, bool ALIGN_EPI = false, bool SP2 = false>
; __device__ __forceinline__ void gemm_phase(PG8_LAS unsigned char* lds, const Gemm g, const Sched& S, const Epi& E) {
;     ...
;             PG8_WAIT_V(8); PG8_WAIT_L(0); PG8_BAR; PG8_MMA(1, 0, At, B0); PG8_MMA(1, 1, At, B1); PG8_BAR; PG8_SCHED;
;             PG8_LDB(B0, 1, 0); PG8_LDB(B1, 1, 1); PG8_SCHED; PG8_LDA(At, 1, 0); PG8_STAGE(PG8_SA(0, 1), a2 + hstep, voffA);
;             PG8_WAIT_V(8); PG8_WAIT_L(0); PG8_BAR; PG8_MMA(0, 0, At, B0); PG8_MMA(0, 1, At, B1); PG8_BAR; PG8_SCHED;
;             PG8_LDA(At, 1, 1); PG8_STAGE(PG8_SB(1, 0), b3, voffB); PG8_STAGE(PG8_SB(1, 1), b3 + hstep, voffB); PG8_STAGE(PG8_SA(1, 0), a3, voffA);
	s_add_i32 s57, 0, 0x18000
	s_add_i32 s58, 0, 0x1c000
	v_add_u32_e32 v156, s57, v1
	v_add_u32_e32 v174, s58, v1
	ds_read_b128 v[144:147], v156
	ds_read_b128 v[148:151], v156 offset:1024
	ds_read_b128 v[152:155], v156 offset:2048
	ds_read_b128 v[156:159], v156 offset:3072
	ds_read_b128 v[160:163], v174
	ds_read_b128 v[166:169], v174 offset:1024
	ds_read_b128 v[170:173], v174 offset:2048
	ds_read_b128 v[174:177], v174 offset:3072
	s_add_u32 s22, s22, s33
	s_addc_u32 s23, s23, 0
	s_mov_b32 m0, s47
	ds_read_b128 v[178:181], v143 offset:32768
	ds_read_b128 v[198:201], v143 offset:33792
	ds_read_b128 v[202:205], v143 offset:34816
	ds_read_b128 v[220:223], v143 offset:35840
	ds_read_b128 v[224:227], v143 offset:36864
	ds_read_b128 v[228:231], v143 offset:37888
	ds_read_b128 v[232:235], v143 offset:38912
	ds_read_b128 v[236:239], v143 offset:39936
	s_add_u32 vcc_lo, s100, 0x20000
	s_addc_u32 vcc_hi, s101, 0
	global_load_lds_dwordx4 v186, vcc
	s_mov_b32 m0, s48
	s_nop 0
	s_add_u32 vcc_lo, s100, 0x30000
	s_addc_u32 vcc_hi, s101, 0
	global_load_lds_dwordx4 v186, vcc
	s_waitcnt vmcnt(8)
	s_waitcnt lgkmcnt(0)
	s_barrier
	s_setprio 1
	s_waitcnt lgkmcnt(0)
	v_mfma_f32_16x16x32_bf16 v[100:103], v[144:147], v[178:181], v[100:103]
	v_mfma_f32_16x16x32_bf16 v[68:71], v[152:155], v[178:181], v[68:71]
	v_mfma_f32_16x16x32_bf16 v[116:119], v[144:147], v[202:205], v[116:119]
	v_mfma_f32_16x16x32_bf16 v[80:83], v[152:155], v[202:205], v[80:83]
	v_mfma_f32_16x16x32_bf16 v[124:127], v[144:147], v[224:227], v[124:127]
	v_mfma_f32_16x16x32_bf16 v[104:107], v[152:155], v[224:227], v[104:107]
	v_mfma_f32_16x16x32_bf16 v[128:131], v[144:147], v[232:235], v[128:131]
	v_mfma_f32_16x16x32_bf16 v[120:123], v[152:155], v[232:235], v[120:123]
	v_mfma_f32_16x16x32_bf16 v[100:103], v[148:151], v[198:201], v[100:103]
	v_mfma_f32_16x16x32_bf16 v[68:71], v[156:159], v[198:201], v[68:71]
	v_mfma_f32_16x16x32_bf16 v[116:119], v[148:151], v[220:223], v[116:119]
	v_mfma_f32_16x16x32_bf16 v[80:83], v[156:159], v[220:223], v[80:83]
	v_mfma_f32_16x16x32_bf16 v[124:127], v[148:151], v[228:231], v[124:127]
	v_mfma_f32_16x16x32_bf16 v[104:107], v[156:159], v[228:231], v[104:107]
	v_mfma_f32_16x16x32_bf16 v[128:131], v[148:151], v[236:239], v[128:131]
	v_mfma_f32_16x16x32_bf16 v[120:123], v[156:159], v[236:239], v[120:123]
	s_setprio 0
	s_setprio 1
	v_mfma_f32_16x16x32_bf16 v[16:19], v[160:163], v[178:181], v[16:19]
	v_mfma_f32_16x16x32_bf16 v[4:7], v[170:173], v[178:181], v[4:7]
	v_mfma_f32_16x16x32_bf16 v[32:35], v[160:163], v[202:205], v[32:35]
	v_mfma_f32_16x16x32_bf16 v[8:11], v[170:173], v[202:205], v[8:11]
	v_mfma_f32_16x16x32_bf16 v[48:51], v[160:163], v[224:227], v[48:51]
	v_mfma_f32_16x16x32_bf16 v[12:15], v[170:173], v[224:227], v[12:15]
	v_mfma_f32_16x16x32_bf16 v[76:79], v[160:163], v[232:235], v[76:79]
	v_mfma_f32_16x16x32_bf16 v[24:27], v[170:173], v[232:235], v[24:27]
	v_mfma_f32_16x16x32_bf16 v[16:19], v[166:169], v[198:201], v[16:19]
	v_mfma_f32_16x16x32_bf16 v[4:7], v[174:177], v[198:201], v[4:7]
	v_mfma_f32_16x16x32_bf16 v[32:35], v[166:169], v[220:223], v[32:35]
	v_mfma_f32_16x16x32_bf16 v[8:11], v[174:177], v[220:223], v[8:11]
	v_mfma_f32_16x16x32_bf16 v[48:51], v[166:169], v[228:231], v[48:51]
	v_mfma_f32_16x16x32_bf16 v[12:15], v[174:177], v[228:231], v[12:15]
	v_mfma_f32_16x16x32_bf16 v[76:79], v[166:169], v[236:239], v[76:79]
	v_mfma_f32_16x16x32_bf16 v[24:27], v[174:177], v[236:239], v[24:27]
	s_setprio 0
	s_barrier
	s_add_i32 s22, s57, s13
	s_mov_b32 m0, s22
	ds_read_b128 v[178:181], v143 offset:49152
	ds_read_b128 v[198:201], v143 offset:50176
	ds_read_b128 v[202:205], v143 offset:51200
	ds_read_b128 v[220:223], v143 offset:52224
	ds_read_b128 v[224:227], v143 offset:53248
	ds_read_b128 v[228:231], v143 offset:54272
	ds_read_b128 v[232:235], v143 offset:55296
	ds_read_b128 v[236:239], v143 offset:56320
	s_add_u32 vcc_lo, s100, 0xc0000
	s_addc_u32 vcc_hi, s101, 0
	global_load_lds_dwordx4 v186, vcc
	s_add_i32 m0, s22, 0x2000
	s_add_i32 s22, s58, s13
	s_add_u32 vcc_lo, s100, 0xd0000
	s_addc_u32 vcc_hi, s101, 0
	global_load_lds_dwordx4 v186, vcc
	s_mov_b32 m0, s22
	s_nop 0
	s_add_u32 vcc_lo, s100, 0xe0000
	s_addc_u32 vcc_hi, s101, 0
	global_load_lds_dwordx4 v186, vcc
	s_add_i32 m0, s22, 0x2000
	s_nop 0
	s_add_u32 vcc_lo, s100, 0xf0000
	s_addc_u32 vcc_hi, s101, 0
	global_load_lds_dwordx4 v186, vcc
	s_mov_b32 m0, s50
	s_nop 0
	s_add_u32 vcc_lo, s100, 0x40000
	s_addc_u32 vcc_hi, s101, 0
	global_load_lds_dwordx4 v186, vcc
	s_mov_b32 m0, s51
	s_nop 0
	s_add_u32 vcc_lo, s100, 0x50000
	s_addc_u32 vcc_hi, s101, 0
	global_load_lds_dwordx4 v186, vcc
	s_waitcnt vmcnt(8)
	s_waitcnt lgkmcnt(0)
	s_barrier
; #define PG8_MMA(ai, bj, At, Bt) do { __builtin_amdgcn_s_setprio(1); _Pragma("unroll") for (int m = 0; m < 4; ++m) _Pragma("unroll") for (int n = 0; n < 2; ++n) _Pragma("unroll") for (int k = 0; k < 2; ++k) \
;         acc[ai][bj][m][n] = __builtin_amdgcn_mfma_f32_16x16x32_bf16(Bt[n][k], At[m][k], acc[ai][bj][m][n], 0, 0, 0); __builtin_amdgcn_s_setprio(0); } while (0)
; #define PG8_WAIT_V(n) asm volatile("s_waitcnt vmcnt(" #n ")" ::: "memory")
; #define PG8_WAIT_L(n) asm volatile("s_waitcnt lgkmcnt(" #n ")" ::: "memory")
; #define PG8_BAR __builtin_amdgcn_s_barrier()
; #define PG8_SCHED __builtin_amdgcn_sched_barrier(0)
; template <class Epi, class Sched, bool ALIGN_EPI = false, bool SP2 = false>
; __device__ __forceinline__ void gemm_phase(PG8_LAS unsigned char* lds, const Gemm g, const Sched& S, const Epi& E) {
;     ...
;             PG8_WAIT_V(8); PG8_WAIT_L(0); PG8_BAR; PG8_MMA(1, 0, At, B0); PG8_MMA(1, 1, At, B1); PG8_BAR; PG8_SCHED;
;     ...
;         if (!has_next) break;
; #pragma unroll
;         for (int a = 0; a < 2; ++a)
; #pragma unroll
;             for (int b = 0; b < 2; ++b)
; #pragma unroll
;                 for (int m = 0; m < 4; ++m)
; #pragma unroll
;                     for (int n = 0; n < 2; ++n) acc[a][b][m][n] = (f32x4){0.f, 0.f, 0.f, 0.f};
;         cur = nxt; cA = nA; cB = nB; ++ui;
	s_setprio 1
	s_waitcnt lgkmcnt(0)
	v_mfma_f32_16x16x32_bf16 v[108:111], v[144:147], v[178:181], v[108:111]
	v_mfma_f32_16x16x32_bf16 v[112:115], v[152:155], v[178:181], v[112:115]
	v_mfma_f32_16x16x32_bf16 v[88:91], v[144:147], v[202:205], v[88:91]
	v_mfma_f32_16x16x32_bf16 v[92:95], v[152:155], v[202:205], v[92:95]
	v_mfma_f32_16x16x32_bf16 v[60:63], v[144:147], v[224:227], v[60:63]
	v_mfma_f32_16x16x32_bf16 v[64:67], v[152:155], v[224:227], v[64:67]
	v_mfma_f32_16x16x32_bf16 v[36:39], v[144:147], v[232:235], v[36:39]
	v_mfma_f32_16x16x32_bf16 v[40:43], v[152:155], v[232:235], v[40:43]
	v_mfma_f32_16x16x32_bf16 v[108:111], v[148:151], v[198:201], v[108:111]
	v_mfma_f32_16x16x32_bf16 v[112:115], v[156:159], v[198:201], v[112:115]
	v_mfma_f32_16x16x32_bf16 v[88:91], v[148:151], v[220:223], v[88:91]
	v_mfma_f32_16x16x32_bf16 v[92:95], v[156:159], v[220:223], v[92:95]
	v_mfma_f32_16x16x32_bf16 v[60:63], v[148:151], v[228:231], v[60:63]
	v_mfma_f32_16x16x32_bf16 v[64:67], v[156:159], v[228:231], v[64:67]
	v_mfma_f32_16x16x32_bf16 v[36:39], v[148:151], v[236:239], v[36:39]
	v_mfma_f32_16x16x32_bf16 v[40:43], v[156:159], v[236:239], v[40:43]
	s_setprio 0
	s_setprio 1
	v_mfma_f32_16x16x32_bf16 v[96:99], v[160:163], v[178:181], v[96:99]
	v_mfma_f32_16x16x32_bf16 v[44:47], v[170:173], v[178:181], v[44:47]
	v_mfma_f32_16x16x32_bf16 v[84:87], v[160:163], v[202:205], v[84:87]
	v_mfma_f32_16x16x32_bf16 v[72:75], v[170:173], v[202:205], v[72:75]
	v_mfma_f32_16x16x32_bf16 v[56:59], v[160:163], v[224:227], v[56:59]
	v_mfma_f32_16x16x32_bf16 v[52:55], v[170:173], v[224:227], v[52:55]
	v_mfma_f32_16x16x32_bf16 v[28:31], v[160:163], v[232:235], v[28:31]
	v_mfma_f32_16x16x32_bf16 v[20:23], v[170:173], v[232:235], v[20:23]
	v_mfma_f32_16x16x32_bf16 v[96:99], v[166:169], v[198:201], v[96:99]
	v_mfma_f32_16x16x32_bf16 v[44:47], v[174:177], v[198:201], v[44:47]
	v_mfma_f32_16x16x32_bf16 v[84:87], v[166:169], v[220:223], v[84:87]
	v_mfma_f32_16x16x32_bf16 v[72:75], v[174:177], v[220:223], v[72:75]
	v_mfma_f32_16x16x32_bf16 v[56:59], v[166:169], v[228:231], v[56:59]
	v_mfma_f32_16x16x32_bf16 v[52:55], v[174:177], v[228:231], v[52:55]
	v_mfma_f32_16x16x32_bf16 v[28:31], v[166:169], v[236:239], v[28:31]
	v_mfma_f32_16x16x32_bf16 v[20:23], v[174:177], v[236:239], v[20:23]
	s_setprio 0
	s_barrier
	s_add_u32 s20, s20, 0x100
	s_addc_u32 s21, s21, 0
	v_lshl_add_u64 v[140:141], v[140:141], 0, s[62:63]
	v_lshl_add_u64 v[138:139], v[138:139], 0, s[62:63]
	s_cmp_ge_u32 s56, s29
	s_mov_b32 s22, s56
	v_readlane_b32 s100, v255, 11
.Lpeel_done:
	s_and_b64 vcc, exec, s[38:39]
	s_cbranch_vccnz .LBB11_1884
	v_mov_b32_e32 v20, 0
	s_mov_b32 s42, s53
	s_mov_b32 s28, s54
	s_mov_b64 s[14:15], s[18:19]
	s_mov_b64 s[16:17], s[4:5]
	s_mov_b32 s52, s55
	v_mov_b32_e32 v21, v20
	v_mov_b32_e32 v22, v20
	v_mov_b32_e32 v23, v20
	v_mov_b32_e32 v28, v20
	v_mov_b32_e32 v29, v20
	v_mov_b32_e32 v30, v20
	v_mov_b32_e32 v31, v20
	v_mov_b32_e32 v52, v20
	v_mov_b32_e32 v53, v20
	v_mov_b32_e32 v54, v20
	v_mov_b32_e32 v55, v20
	v_mov_b32_e32 v56, v20
	v_mov_b32_e32 v57, v20
	v_mov_b32_e32 v58, v20
	v_mov_b32_e32 v59, v20
	v_mov_b32_e32 v72, v20
	v_mov_b32_e32 v73, v20
	v_mov_b32_e32 v74, v20
	v_mov_b32_e32 v75, v20
	v_mov_b32_e32 v84, v20
	v_mov_b32_e32 v85, v20
	v_mov_b32_e32 v86, v20
	v_mov_b32_e32 v87, v20
	v_mov_b32_e32 v44, v20
	v_mov_b32_e32 v45, v20
	v_mov_b32_e32 v46, v20
	v_mov_b32_e32 v47, v20
	v_mov_b32_e32 v96, v20
	v_mov_b32_e32 v97, v20
	v_mov_b32_e32 v98, v20
	v_mov_b32_e32 v99, v20
	v_mov_b32_e32 v40, v20
	v_mov_b32_e32 v41, v20
	v_mov_b32_e32 v42, v20
	v_mov_b32_e32 v43, v20
	v_mov_b32_e32 v36, v20
	v_mov_b32_e32 v37, v20
	v_mov_b32_e32 v38, v20
	v_mov_b32_e32 v39, v20
	v_mov_b32_e32 v64, v20
	v_mov_b32_e32 v65, v20
	v_mov_b32_e32 v66, v20
	v_mov_b32_e32 v67, v20
	v_mov_b32_e32 v60, v20
	v_mov_b32_e32 v61, v20
	v_mov_b32_e32 v62, v20
	v_mov_b32_e32 v63, v20
	v_mov_b32_e32 v92, v20
	v_mov_b32_e32 v93, v20
	v_mov_b32_e32 v94, v20
	v_mov_b32_e32 v95, v20
	v_mov_b32_e32 v88, v20
	v_mov_b32_e32 v89, v20
	v_mov_b32_e32 v90, v20
	v_mov_b32_e32 v91, v20
	v_mov_b32_e32 v112, v20
	v_mov_b32_e32 v113, v20
	v_mov_b32_e32 v114, v20
	v_mov_b32_e32 v115, v20
	v_mov_b32_e32 v108, v20
	v_mov_b32_e32 v109, v20
	v_mov_b32_e32 v110, v20
	v_mov_b32_e32 v111, v20
	v_mov_b32_e32 v24, v20
	v_mov_b32_e32 v25, v20
	v_mov_b32_e32 v26, v20
	v_mov_b32_e32 v27, v20
	v_mov_b32_e32 v76, v20
	v_mov_b32_e32 v77, v20
	v_mov_b32_e32 v78, v20
	v_mov_b32_e32 v79, v20
	v_mov_b32_e32 v12, v20
	v_mov_b32_e32 v13, v20
	v_mov_b32_e32 v14, v20
	v_mov_b32_e32 v15, v20
	v_mov_b32_e32 v48, v20
	v_mov_b32_e32 v49, v20
	v_mov_b32_e32 v50, v20
	v_mov_b32_e32 v51, v20
	v_mov_b32_e32 v8, v20
	v_mov_b32_e32 v9, v20
	v_mov_b32_e32 v10, v20
	v_mov_b32_e32 v11, v20
	v_mov_b32_e32 v32, v20
	v_mov_b32_e32 v33, v20
	v_mov_b32_e32 v34, v20
	v_mov_b32_e32 v35, v20
	v_mov_b32_e32 v4, v20
	v_mov_b32_e32 v5, v20
	v_mov_b32_e32 v6, v20
	v_mov_b32_e32 v7, v20
	v_mov_b32_e32 v16, v20
	v_mov_b32_e32 v17, v20
	v_mov_b32_e32 v18, v20
	v_mov_b32_e32 v19, v20
	v_mov_b32_e32 v120, v20
	v_mov_b32_e32 v121, v20
	v_mov_b32_e32 v122, v20
	v_mov_b32_e32 v123, v20
	v_mov_b32_e32 v128, v20
	v_mov_b32_e32 v129, v20
	v_mov_b32_e32 v130, v20
	v_mov_b32_e32 v131, v20
	v_mov_b32_e32 v104, v20
	v_mov_b32_e32 v105, v20
	v_mov_b32_e32 v106, v20
	v_mov_b32_e32 v107, v20
	v_mov_b32_e32 v124, v20
	v_mov_b32_e32 v125, v20
	v_mov_b32_e32 v126, v20
	v_mov_b32_e32 v127, v20
	v_mov_b32_e32 v80, v20
	v_mov_b32_e32 v81, v20
	v_mov_b32_e32 v82, v20
	v_mov_b32_e32 v83, v20
	v_mov_b32_e32 v116, v20
	v_mov_b32_e32 v117, v20
	v_mov_b32_e32 v118, v20
	v_mov_b32_e32 v119, v20
	v_mov_b32_e32 v68, v20
	v_mov_b32_e32 v69, v20
	v_mov_b32_e32 v70, v20
	v_mov_b32_e32 v71, v20
	v_mov_b32_e32 v100, v20
	v_mov_b32_e32 v101, v20
	v_mov_b32_e32 v102, v20
	v_mov_b32_e32 v103, v20
	s_branch .LBB11_1884

; #define PG8_LAS __attribute__((address_space(3)))
;     __device__ __forceinline__ void fused(f32x4 (&acc)[2][2][4][2], const Unit& u, int wr, int wc, int fr, int fq, PG8_LAS unsigned char* lds, int wid, int lane) const {
;     ...
;         if (!Xin) {
; #pragma unroll
;             for (int i = 0; i < 16; ++i) { const int c = wid * 16 + i, row = 2 * c + (lane >> 5), p = (lane & 31) ^ (row & 15);
;                 const bf16_t* src = XB + (size_t)(u.pm * BM + row) * ldc + u.pn * BM + p * 8;
;                 __builtin_amdgcn_global_load_lds((const unsigned*)src, (PG8_LAS unsigned*)(lds + c * 1024), 16, 0, 0); }
;             asm volatile("s_waitcnt vmcnt(0)" ::: "memory"); __builtin_amdgcn_s_barrier(); asm volatile("" ::: "memory");
;         }
.LBB11_1903:
	s_mov_b64 s[14:15], 0x47a00000
	v_lshl_add_u64 v[156:157], v[140:141], 0, s[14:15]
	s_lshl_b32 s14, s42, 8
	v_bfe_u32 v144, v142, 5, 1
	s_andn2_b64 vcc, exec, s[16:17]
	v_and_b32_e32 v167, 31, v142
	s_cbranch_vccnz .LBB11_1905
	s_lshl_b32 s22, s28, 8
	s_lshl_b32 s13, s25, 1
	v_add_u32_e32 v140, s13, v144
	v_xor_b32_e32 v141, v167, v140
	v_lshlrev_b32_e32 v141, 4, v141
	v_lshl_add_u32 v142, v140, 12, v141
	v_mov_b32_e32 v143, 0
	s_lshl_b32 s16, s22, 12
	s_lshl_b32 s13, s14, 1
	s_add_u32 s16, s16, s13
	s_add_u32 s16, s16, 0x60000
	s_mov_b32 s17, 0
	v_lshl_add_u64 v[140:141], v[156:157], 0, v[142:143]
	v_lshl_add_u64 v[140:141], v[140:141], 0, s[16:17]
	s_lshl_b32 s13, s25, 10
	s_add_i32 m0, s13, 0xc000
	s_mov_b64 s[16:17], 0x10000
	global_load_lds_dwordx4 v[140:141], off
	v_lshl_add_u64 v[140:141], v[140:141], 0, s[16:17]
	s_add_i32 m0, s13, 0xe000
	s_nop 0
	global_load_lds_dwordx4 v[140:141], off
	s_waitcnt vmcnt(0)
	s_barrier
